# P2: waves 4-7 run the memory-bound short conv before the VALU-bound conformer conv so the two overlap
# speedup vs baseline: 1.0015x; 1.0015x over previous
; #define LAS __attribute__((address_space(3)))
; __device__ __forceinline__ void conv_a_wave(const bf16* U0, const float* cwp, const float* cb, const float* lg, const float* lb, bf16* MIX, LAS unsigned* T, int it0, int step, int nitems, int lane) {
;     const int lr = lane >> 4, lc = lane & 15;
;     int cur_grp = -1; f32x2 w[CONVK]; f32x2 bias = (f32x2){0.f, 0.f}, gg = bias, bb = bias;
; #pragma unroll
;     for (int k = 0; k < CONVK; ++k) w[k] = (f32x2){0.f, 0.f};
;     for (int item = it0; item < nitems; item += step) {
;         const int tb = item >> 4, grp = item & 15, r0 = tb * 32; const bool first = (r0 % SEQ) == 0;
;         u32x4 v[16];
; #pragma unroll
;         for (int p = 0; p < 16; ++p) { const int rr = 4 * p + lr; v[p] = (u32x4){0u, 0u, 0u, 0u};
; __global__ void __launch_bounds__(NWAVES * 64, 2) fwd_kernel(Args args) {
;     ...
;         _Pragma("nounroll") for (int rep2_ = 0; rep2_ <= ((DUP_MASK >> 2) & 1); ++rep2_) {
;         { LAS unsigned* T = (LAS unsigned*)(lds + wave * 15872);
;           conv_a_wave(U0, conv_a_w, conv_a_b, ln_a_g, ln_a_b, MIX, T, gw, NGW, (MTOK / 32) * 16, lane); }
;         for (size_t i = (size_t)vcu * 512 + tid; i < (size_t)(MTOK / 4) * (CWID / 8); i += (size_t)G * 512) {
.LBB0_626:
	v_readlane_b32 s36, v244, 2
	v_readlane_b32 s50, v244, 16
	v_readlane_b32 s51, v244, 17
	s_add_u32 s60, s50, 0x3a600000
	s_addc_u32 s61, s51, 0
	s_add_u32 s21, s50, 0x27500000
	s_addc_u32 s0, s51, 0
	s_add_u32 s88, s50, 0x29500000
	v_readlane_b32 s37, v244, 3
	v_readlane_b32 s38, v244, 4
	v_readlane_b32 s39, v244, 5
	v_readlane_b32 s40, v244, 6
	v_readlane_b32 s41, v244, 7
	v_readlane_b32 s42, v244, 8
	v_readlane_b32 s43, v244, 9
	v_readlane_b32 s44, v244, 10
	v_readlane_b32 s45, v244, 11
	v_readlane_b32 s46, v244, 12
	v_readlane_b32 s47, v244, 13
	v_readlane_b32 s48, v244, 14
	v_readlane_b32 s49, v244, 15
	v_writelane_b32 v244, s0, 51
	s_addc_u32 s0, s51, 0
	s_mov_b32 s98, 0
	s_cmp_lt_i32 s96, 3
	v_writelane_b32 v244, s0, 53
	s_cselect_b64 s[0:1], -1, 0
	s_cmp_gt_i32 s97, 2
	s_cselect_b64 s[2:3], -1, 0
	s_and_b64 s[0:1], s[0:1], s[2:3]
	s_andn2_b64 vcc, exec, s[0:1]
	s_cbranch_vccnz .LBB0_762
.Lmy_conv_entry:
	v_readlane_b32 s99, v244, 42
	s_nop 3
	s_cmp_lt_u32 s99, 4
	s_cbranch_scc1 .Lmy_conv_a
	s_cmp_lg_u32 s98, 0
	s_cbranch_scc1 .Lmy_conv_a
	s_mov_b32 s98, 1
	v_and_b32_e32 v1, 15, v0
	s_branch .LBB0_653
.Lmy_conv_a:
	s_cmpk_gt_i32 s18, 0x1fff
	v_and_b32_e32 v1, 15, v0
	s_cbranch_scc1 .LBB0_653
	v_readlane_b32 s1, v244, 42
	s_waitcnt vmcnt(47)
	v_and_b32_e32 v4, 63, v0
	s_mul_i32 s0, s1, 0x3e00
	v_mov_b32_e32 v103, 0
	v_readlane_b32 s36, v244, 2
	v_bfe_u32 v148, v0, 4, 2
	s_add_i32 s0, s0, 0
	v_lshlrev_b32_e32 v102, 4, v1
	v_readlane_b32 s48, v244, 14
	v_readlane_b32 s49, v244, 15
	v_lshlrev_b32_e32 v2, 3, v4
	v_mov_b32_e32 v3, v103
	v_lshl_add_u64 v[66:67], s[48:49], 0, v[102:103]
	v_lshl_add_u64 v[68:69], s[76:77], 0, v[2:3]
	v_lshl_add_u64 v[70:71], s[78:79], 0, v[2:3]
	v_lshl_add_u64 v[72:73], s[80:81], 0, v[2:3]
	v_lshl_add_u64 v[74:75], s[82:83], 0, v[2:3]
	v_add_u32_e32 v2, s0, v102
	v_lshlrev_b32_e32 v102, 2, v4
	v_or_b32_e32 v150, 4, v148
	v_or_b32_e32 v151, 8, v148
	v_or_b32_e32 v152, 12, v148
	v_or_b32_e32 v153, 16, v148
	v_or_b32_e32 v154, 20, v148
	v_or_b32_e32 v155, 24, v148
	v_or_b32_e32 v156, 28, v148
	v_or_b32_e32 v157, 32, v148
	v_or_b32_e32 v158, 36, v148
	v_or_b32_e32 v159, 40, v148
	v_or_b32_e32 v160, 44, v148
	v_or_b32_e32 v161, 48, v148
	v_or_b32_e32 v162, 52, v148
	v_or_b32_e32 v163, 56, v148
	v_or_b32_e32 v164, 60, v148
	v_add_u32_e32 v149, s0, v102
	v_lshl_add_u64 v[76:77], s[60:61], 0, v[102:103]
	v_lshlrev_b32_e32 v3, 8, v148
	v_lshlrev_b32_e32 v4, 8, v150
	v_lshlrev_b32_e32 v5, 8, v151
	s_waitcnt vmcnt(46)
	v_lshlrev_b32_e32 v6, 8, v152
	v_lshlrev_b32_e32 v7, 8, v153
	v_lshlrev_b32_e32 v8, 8, v154
	v_lshlrev_b32_e32 v9, 8, v155
	s_waitcnt vmcnt(45)
	v_lshlrev_b32_e32 v10, 8, v156
	v_lshlrev_b32_e32 v11, 8, v157
	v_lshlrev_b32_e32 v12, 8, v158
	v_lshlrev_b32_e32 v13, 8, v159
	s_waitcnt vmcnt(44)
	v_lshlrev_b32_e32 v14, 8, v160
	v_lshlrev_b32_e32 v15, 8, v161
	v_lshlrev_b32_e32 v16, 8, v162
	v_lshlrev_b32_e32 v17, 8, v163
	s_waitcnt vmcnt(41)
	v_lshlrev_b32_e32 v18, 8, v164
	s_lshl_b32 s0, s34, 4
	s_lshl_b32 s1, s1, 1
	v_mov_b32_e32 v102, v103
	s_mov_b32 s55, 0
	v_cmp_gt_u32_e64 s[64:65], 30, v156
	v_cmp_gt_u32_e64 s[2:3], 62, v164
	s_add_i32 s14, s0, s1
	s_lshl_b32 s15, s22, 4
	s_mov_b32 s27, -1
	v_add_u32_e32 v165, v2, v3
	v_add_u32_e32 v166, v2, v4
	v_add_u32_e32 v167, v2, v5
	v_add_u32_e32 v168, v2, v6
	v_add_u32_e32 v169, v2, v7
	v_add_u32_e32 v170, v2, v8
	v_add_u32_e32 v171, v2, v9
	v_add_u32_e32 v172, v2, v10
	v_add_u32_e32 v173, v2, v11
	v_add_u32_e32 v174, v2, v12
	v_add_u32_e32 v175, v2, v13
	v_add_u32_e32 v176, v2, v14
	v_add_u32_e32 v177, v2, v15
	v_add_u32_e32 v178, v2, v16
	v_add_u32_e32 v179, v2, v17
	v_add_u32_e32 v180, v2, v18
	v_mov_b32_e32 v181, 0x358637bd
	s_mov_b32 s23, 0xf800000
	v_mov_b32_e32 v182, 0x260
	v_mov_b64_e32 v[136:137], v[102:103]
	v_mov_b64_e32 v[138:139], v[102:103]
	v_mov_b64_e32 v[134:135], v[102:103]
	v_mov_b64_e32 v[128:129], v[102:103]
	v_mov_b64_e32 v[130:131], v[102:103]
	v_mov_b64_e32 v[132:133], v[102:103]
	v_mov_b64_e32 v[126:127], v[102:103]
	v_mov_b64_e32 v[120:121], v[102:103]
	v_mov_b64_e32 v[122:123], v[102:103]
	v_mov_b64_e32 v[124:125], v[102:103]
	v_mov_b64_e32 v[118:119], v[102:103]
	v_mov_b64_e32 v[112:113], v[102:103]
	v_mov_b64_e32 v[114:115], v[102:103]
	v_mov_b64_e32 v[116:117], v[102:103]
	v_mov_b64_e32 v[110:111], v[102:103]
	v_mov_b64_e32 v[104:105], v[102:103]
	v_mov_b64_e32 v[106:107], v[102:103]
	v_mov_b64_e32 v[108:109], v[102:103]
	v_mov_b64_e32 v[100:101], v[102:103]
	v_mov_b64_e32 v[94:95], v[102:103]
	v_mov_b64_e32 v[96:97], v[102:103]
	v_mov_b64_e32 v[98:99], v[102:103]
	v_mov_b64_e32 v[92:93], v[102:103]
	v_mov_b64_e32 v[86:87], v[102:103]
	v_mov_b64_e32 v[88:89], v[102:103]
	v_mov_b64_e32 v[90:91], v[102:103]
	v_mov_b64_e32 v[84:85], v[102:103]
	v_mov_b64_e32 v[78:79], v[102:103]
	v_mov_b64_e32 v[80:81], v[102:103]
	v_mov_b64_e32 v[82:83], v[102:103]
	v_mov_b64_e32 v[140:141], v[102:103]
	v_mov_b64_e32 v[142:143], v[102:103]
	v_mov_b64_e32 v[144:145], v[102:103]
	s_mov_b32 s26, s18
	v_readlane_b32 s37, v244, 3
	v_readlane_b32 s38, v244, 4
	v_readlane_b32 s39, v244, 5
	v_readlane_b32 s40, v244, 6
	v_readlane_b32 s41, v244, 7
	v_readlane_b32 s42, v244, 8
	v_readlane_b32 s43, v244, 9
	v_readlane_b32 s44, v244, 10
	v_readlane_b32 s45, v244, 11
	v_readlane_b32 s46, v244, 12
	v_readlane_b32 s47, v244, 13
	v_readlane_b32 s50, v244, 16
	v_readlane_b32 s51, v244, 17
	s_branch .LBB0_630

; #define GAS __attribute__((address_space(1)))
; __global__ void __launch_bounds__(NWAVES * 64, 2) fwd_kernel(Args args) {
;     ...
;         for (size_t i = (size_t)vcu * 512 + tid; i < (size_t)(MTOK / 4) * (CWID / 8); i += (size_t)G * 512) {
;             const int rq = (int)(i >> 8), ch = (int)(i & 255), row0 = rq * 4; const bool first = (row0 % SEQ) == 0;
;             const u32x4 z4 = (u32x4){0u, 0u, 0u, 0u};
;             u32x4 cv[6], bg[4];
; #pragma unroll
;             for (int r = 0; r < 6; ++r) cv[r] = (first && r < 2) ? z4 : *(const GAS u32x4*)(CH + (size_t)(row0 - 2 + r) * CWID + ch * 8);
; #pragma unroll
;             for (int r = 0; r < 4; ++r) bg[r] = *(const GAS u32x4*)(BG + (size_t)(row0 + r) * CWID + ch * 8);
;             float w0[8], w1[8], w2[8];
; #pragma unroll
;             for (int h = 0; h < 2; ++h) { const f32x4 a = *(const GAS f32x4*)(conv_b_w + ch * 8 + 4 * h), b = *(const GAS f32x4*)(conv_b_w + CWID + ch * 8 + 4 * h), c = *(const GAS f32x4*)(conv_b_w + 2 * CWID + ch * 8 + 4 * h);
.LBB0_653:
	s_ashr_i32 s35, s34, 31
	s_lshl_b64 s[0:1], s[34:35], 9
	s_waitcnt vmcnt(36)
	v_or_b32_e32 v42, s0, v0
	v_mov_b32_e32 v43, s1
	s_mov_b64 s[0:1], 0x100000
	v_cmp_gt_u64_e32 vcc, s[0:1], v[42:43]
	s_ashr_i32 s23, s22, 31
	s_nop 1
	s_cmp_eq_u32 s98, 2
	s_cselect_b64 vcc, 0, vcc
	s_and_saveexec_b64 s[2:3], vcc
	s_cbranch_execz .LBB0_660
	v_lshlrev_b32_e32 v2, 3, v0
	v_and_b32_e32 v2, 0x7f8, v2
	v_readlane_b32 s0, v244, 47
	v_mov_b32_e32 v45, 0
	v_lshlrev_b32_e32 v44, 1, v2
	v_readlane_b32 s1, v244, 48
	v_readlane_b32 s36, v244, 23
	v_readlane_b32 s37, v244, 24
	v_lshl_add_u64 v[46:47], s[0:1], 0, v[44:45]
	v_readlane_b32 s0, v244, 49
	v_readlane_b32 s1, v244, 50
	s_lshl_b64 s[4:5], s[22:23], 9
	s_mov_b64 s[10:11], 0
	v_lshl_add_u64 v[48:49], s[0:1], 0, v[44:45]
	v_lshlrev_b32_e32 v44, 2, v2
	s_waitcnt vmcnt(35)
	v_lshl_add_u64 v[50:51], s[36:37], 0, v[44:45]
	s_mov_b64 s[0:1], 0x2000
	v_lshl_add_u64 v[52:53], v[50:51], 0, s[0:1]
	s_mov_b64 s[0:1], 0x4000
	s_waitcnt vmcnt(34)
	v_lshl_add_u64 v[54:55], v[50:51], 0, s[0:1]
	s_movk_i32 s6, 0x1000
	v_lshlrev_b32_e32 v56, 1, v2
	v_mov_b32_e32 v57, v45
	s_mov_b64 s[52:53], 0xfffff
	v_readlane_b32 s38, v244, 25
	v_readlane_b32 s39, v244, 26
	v_readlane_b32 s40, v244, 27
	v_readlane_b32 s41, v244, 28
	v_readlane_b32 s42, v244, 29
	v_readlane_b32 s43, v244, 30
	v_readlane_b32 s44, v244, 31
	v_readlane_b32 s45, v244, 32
	v_readlane_b32 s46, v244, 33
	v_readlane_b32 s47, v244, 34
	v_readlane_b32 s48, v244, 35
	v_readlane_b32 s49, v244, 36
	v_readlane_b32 s50, v244, 37
	v_readlane_b32 s51, v244, 38
	s_branch .LBB0_656

; #define REPS(k) _Pragma("unroll") for (int rep_ = 0; rep_ <= ((DUP_MASK >> (k)) & 1); ++rep_)
;     const int tid = threadIdx.x, wid = __builtin_amdgcn_readfirstlane(tid >> 6), lane = tid & 63, wr = wid >> 2, wc = wid & 3, fr = lane & 15, fq = lane >> 4;
;     const int K = g.K, nt = K / BK;
;     unsigned voffA[2], voffB[2];
; #pragma unroll
;     for (int i = 0; i < 2; ++i) { int R, C; stage_rc(tid * 16 + i * 8192, R, C); const int Rb = Epi::PERM ? ((R & ~31) + perm32(R & 31)) : R;
;         voffA[i] = (unsigned)(R * g.lda + C) * 2u; voffB[i] = (unsigned)(Rb * g.ldb + C) * 2u; }
;     const size_t kstep = (size_t)(BK * 2);
;     const size_t hstepA = (size_t)HALF * g.lda * 2, hstepB = (size_t)HALF * g.ldb * 2;
;     const unsigned ldsw = (unsigned)wid * 1024u;
;     const unsigned ldsbase = (unsigned)__builtin_amdgcn_readfirstlane((int)((unsigned)(size_t)lds + ldsw)); (void)ldsw;
;     const int aoff = lds_byte(wr * 64 + fr, fq * 8), boff = lds_byte(wc * 32 + fr, fq * 8);
;     ...
;     Unit cur, nxt; int ui = 0;
;     if (!S.next(0, cur)) return;
;     f32x4 acc[2][2][4][2];
; #pragma unroll
;     for (int a = 0; a < 2; ++a)
; #pragma unroll
;         for (int b = 0; b < 2; ++b)
; #pragma unroll
;             for (int m = 0; m < 4; ++m)
; #pragma unroll
;                 for (int n = 0; n < 2; ++n) acc[a][b][m][n] = (f32x4){0.f, 0.f, 0.f, 0.f};
;     bf16x8 At[4][2], B0[2][2], B1[2][2];
;     if constexpr (VAR >= 2) {
; #pragma unroll
;         for (int m = 0; m < 4; ++m)
; #pragma unroll
;             for (int k = 0; k < 2; ++k) { const unsigned h_ = (unsigned)(tid * 2654435761u + (m * 2 + k) * 40503u); const u32x4 q_ = (u32x4){h_ & 0x3fff3fffu, (h_ * 3u) & 0x3fff3fffu, (h_ * 5u) & 0x3fff3fffu, (h_ * 7u) & 0x3fff3fffu}; At[m][k] = __builtin_bit_cast(bf16x8, q_);
;                 if (m < 2) { B0[m][k] = __builtin_bit_cast(bf16x8, q_ ^ 0x01010101u); B1[m][k] = __builtin_bit_cast(bf16x8, q_ ^ 0x02040204u); } }
;     }
;     const char* cA = unitA(g, cur); const char* cB = unitB(g, cur);
; __global__ void __launch_bounds__(NWAVES * 64, 2) fwd_kernel(Args args) {
;     ...
;         }
;         __syncthreads(); }
;         REPS(10) {
;         { pg8::Gemm g{KV, WQ, 2 * DM, DM, HDIM, 4, 1 << 30, (size_t)MEMLEN * 2 * DM, (size_t)HDIM, 0, (size_t)HDIM, 0}; pg8::BatchOrder S; S.init(1, DM / 256, 16, G, vcu);
.LBB0_660:
	s_or_b64 exec, exec, s[2:3]
	s_cmp_lg_u32 s98, 1
	s_cbranch_scc1 .Lmy_conv_done
	s_mov_b32 s98, 2
	s_branch .Lmy_conv_entry
.Lmy_conv_done:
	v_lshlrev_b32_e32 v2, 4, v0
	v_and_b32_e32 v3, 32, v0
	v_bitop3_b32 v2, v2, v3, 48 bitop3:0x6c
	v_and_or_b32 v173, v0, 64, v2
	v_lshrrev_b32_e32 v2, 5, v0
	v_lshrrev_b32_e32 v5, 1, v0
	v_and_b32_e32 v2, 4, v2
	v_bfe_u32 v3, v0, 2, 2
	v_and_b32_e32 v170, 24, v5
	v_bfe_u32 v4, v0, 2, 4
	v_or3_b32 v2, v2, v3, v170
	v_lshrrev_b32_e32 v3, 3, v0
	v_and_or_b32 v175, v3, 48, v4
	v_and_or_b32 v174, v3, 32, v2
	v_bfe_u32 v3, v0, 3, 25
	v_or_b32_e32 v3, 64, v3
	s_movk_i32 s0, 0x70
	v_and_or_b32 v176, v3, s0, v4
	s_movk_i32 s0, 0x60
	s_cmpk_lt_i32 s34, 0x100
	v_and_or_b32 v177, v3, s0, v2
	s_cselect_b64 s[62:63], -1, 0
	s_lshr_b32 s0, s35, 28
	s_add_i32 s0, s34, s0
	s_ashr_i32 s14, s0, 4
	s_and_b32 s0, s0, -16
	s_sub_i32 s10, s34, s0
	s_lshr_b32 s0, s35, 26
	s_lshr_b32 s2, s14, 30
	s_add_i32 s0, s34, s0
	s_add_i32 s2, s14, s2
	s_ashr_i32 s0, s0, 6
	s_and_b32 s2, s2, -4
	v_lshlrev_b32_e32 v2, 6, v0
	v_lshlrev_b32_e32 v3, 2, v0
	s_ashr_i32 s1, s0, 31
	s_sub_i32 s2, s14, s2
	v_lshlrev_b32_e32 v172, 1, v170
	v_and_b32_e32 v2, 0x3c0, v2
	v_and_b32_e32 v3, 32, v3
	s_ashr_i32 s3, s2, 31
	s_ashr_i32 s11, s10, 31
	s_lshl_b64 s[64:65], s[0:1], 22
	v_readfirstlane_b32 s0, v0
	v_bitop3_b32 v171, v172, v3, v2 bitop3:0x36
	s_lshl_b64 s[54:55], s[2:3], 10
	s_lshl_b64 s[52:53], s[10:11], 21
	s_lshr_b32 s1, s0, 6
	s_and_b64 vcc, exec, s[62:63]
	s_barrier
	s_cbranch_vccz .LBB0_688
	s_lshl_b32 s3, s1, 10
	v_readlane_b32 s36, v244, 2
	s_lshr_b32 s2, s0, 8
	s_add_i32 s15, s3, 0
	v_readlane_b32 s50, v244, 16
	v_readlane_b32 s51, v244, 17
	s_add_u32 s17, s50, 0x13100000
	s_addc_u32 s19, s51, 0
	s_lshl_b64 s[6:7], s[54:55], 1
	s_add_u32 s3, s17, s6
	s_addc_u32 s5, s19, s7
	s_add_u32 s4, s3, s52
	s_addc_u32 s5, s5, s53
	s_add_i32 s24, s15, 0x10000
	s_add_i32 s25, s15, 0x12000
	s_add_u32 s3, s8, s64
	s_addc_u32 s26, s9, s65
	s_add_u32 s78, s3, s6
	v_lshl_or_b32 v179, v174, 13, v173
	s_mov_b32 m0, s24
	s_nop 0
	global_load_lds_dwordx4 v179, s[4:5]
	s_addc_u32 s79, s26, s7
	v_lshl_or_b32 v181, v177, 13, v173
	s_mov_b32 m0, s25
	s_nop 0
	global_load_lds_dwordx4 v181, s[4:5]
	s_add_u32 s6, s4, 0x100000
	s_addc_u32 s7, s5, 0
	s_add_i32 s26, s15, 0x14000
	s_mov_b32 m0, s26
	s_nop 0
	global_load_lds_dwordx4 v179, s[6:7]
	s_add_i32 s27, s15, 0x16000
	s_mov_b32 m0, s27
	s_nop 0
	global_load_lds_dwordx4 v181, s[6:7]
	v_lshl_or_b32 v178, v175, 14, v173
	s_mov_b32 m0, s15
	s_nop 0
	global_load_lds_dwordx4 v178, s[78:79]
	s_add_i32 s28, s15, 0x2000
	v_lshl_or_b32 v180, v176, 14, v173
	s_mov_b32 m0, s28
	s_nop 0
	global_load_lds_dwordx4 v180, s[78:79]
	s_add_u32 s6, s78, 0x200000
	s_addc_u32 s7, s79, 0
	s_add_i32 s29, s15, 0x4000
	s_mov_b32 m0, s29
	s_nop 0
	global_load_lds_dwordx4 v178, s[6:7]
	s_add_i32 s30, s15, 0x6000
	s_mov_b32 m0, s30
	s_nop 0
	global_load_lds_dwordx4 v180, s[6:7]
	s_cmp_eq_u32 s2, 1
	s_mov_b32 s11, 0
	s_cselect_b64 s[66:67], -1, 0
	s_cmp_lg_u32 s2, 1
	v_readlane_b32 s37, v244, 3
	v_readlane_b32 s38, v244, 4
	v_readlane_b32 s39, v244, 5
	v_readlane_b32 s40, v244, 6
	v_readlane_b32 s41, v244, 7
	v_readlane_b32 s42, v244, 8
	v_readlane_b32 s43, v244, 9
	v_readlane_b32 s44, v244, 10
	v_readlane_b32 s45, v244, 11
	v_readlane_b32 s46, v244, 12
	v_readlane_b32 s47, v244, 13
	v_readlane_b32 s48, v244, 14
	v_readlane_b32 s49, v244, 15
	s_cbranch_scc1 .LBB0_663
	s_barrier

; __global__ void __launch_bounds__(NWAVES * 64, 2) fwd_kernel(Args args) {
	.amdhsa_kernel _Z10fwd_kernel4Args
		.amdhsa_group_segment_fixed_size 0
		.amdhsa_private_segment_fixed_size 0
		.amdhsa_kernarg_size 456
		.amdhsa_user_sgpr_count 2
		.amdhsa_user_sgpr_dispatch_ptr 0
		.amdhsa_user_sgpr_queue_ptr 0
		.amdhsa_user_sgpr_kernarg_segment_ptr 1
		.amdhsa_user_sgpr_dispatch_id 0
		.amdhsa_user_sgpr_kernarg_preload_length 0
		.amdhsa_user_sgpr_kernarg_preload_offset 0
		.amdhsa_user_sgpr_private_segment_size 0
		.amdhsa_uses_dynamic_stack 0
		.amdhsa_enable_private_segment 0
		.amdhsa_system_sgpr_workgroup_id_x 1
		.amdhsa_system_sgpr_workgroup_id_y 0
		.amdhsa_system_sgpr_workgroup_id_z 0
		.amdhsa_system_sgpr_workgroup_info 0
		.amdhsa_system_vgpr_workitem_id 0
		.amdhsa_next_free_vgpr 245
		.amdhsa_next_free_sgpr 100
		.amdhsa_accum_offset 248
		.amdhsa_reserve_vcc 1
		.amdhsa_float_round_mode_32 0
		.amdhsa_float_round_mode_16_64 0
		.amdhsa_float_denorm_mode_32 3
		.amdhsa_float_denorm_mode_16_64 3
		.amdhsa_dx10_clamp 1
		.amdhsa_ieee_mode 1
		.amdhsa_fp16_overflow 0
		.amdhsa_tg_split 0
		.amdhsa_exception_fp_ieee_invalid_op 0
		.amdhsa_exception_fp_denorm_src 0
		.amdhsa_exception_fp_ieee_div_zero 0
		.amdhsa_exception_fp_ieee_overflow 0
		.amdhsa_exception_fp_ieee_underflow 0
		.amdhsa_exception_fp_ieee_inexact 0
		.amdhsa_exception_int_div_zero 0
	.end_amdhsa_kernel

; __global__ void __launch_bounds__(NWAVES * 64, 2) fwd_kernel(Args args) {
amdhsa.kernels:
  - .agpr_count:     0
    .args:
      - .offset:         0
        .size:           200
        .value_kind:     by_value
      - .offset:         200
        .size:           4
        .value_kind:     hidden_block_count_x
      - .offset:         204
        .size:           4
        .value_kind:     hidden_block_count_y
      - .offset:         208
        .size:           4
        .value_kind:     hidden_block_count_z
      - .offset:         212
        .size:           2
        .value_kind:     hidden_group_size_x
      - .offset:         214
        .size:           2
        .value_kind:     hidden_group_size_y
      - .offset:         216
        .size:           2
        .value_kind:     hidden_group_size_z
      - .offset:         218
        .size:           2
        .value_kind:     hidden_remainder_x
      - .offset:         220
        .size:           2
        .value_kind:     hidden_remainder_y
      - .offset:         222
        .size:           2
        .value_kind:     hidden_remainder_z
      - .offset:         240
        .size:           8
        .value_kind:     hidden_global_offset_x
      - .offset:         248
        .size:           8
        .value_kind:     hidden_global_offset_y
      - .offset:         256
        .size:           8
        .value_kind:     hidden_global_offset_z
      - .offset:         264
        .size:           2
        .value_kind:     hidden_grid_dims
      - .offset:         320
        .size:           4
        .value_kind:     hidden_dynamic_lds_size
    .group_segment_fixed_size: 0
    .kernarg_segment_align: 8
    .kernarg_segment_size: 456
    .language:       OpenCL C
    .language_version:
      - 2
      - 0
    .max_flat_workgroup_size: 512
    .name:           _Z10fwd_kernel4Args
    .private_segment_fixed_size: 0
    .sgpr_count:     106
    .sgpr_spill_count: 63
    .symbol:         _Z10fwd_kernel4Args.kd
    .uniform_work_group_size: 1
    .uses_dynamic_stack: false
    .vgpr_count:     245
    .vgpr_spill_count: 0
    .wavefront_size: 64
